# two row-halves FFN, no grid barrier between FFN-out half0 and FFN-in half1 (independent rows)
# speedup vs baseline: 1.0018x; 1.0018x over previous
.LBB0_356:
	s_add_i32 s0, s72, 1
	s_cmp_ge_i32 s0, s75
	s_cselect_b64 s[6:7], -1, 0
	s_cmp_lt_i32 s0, s75
	s_cselect_b64 s[8:9], -1, 0
	s_add_i32 s47, s47, -9
	s_cmp_lt_u32 s47, -2
	s_cselect_b64 s[10:11], -1, 0
	s_and_b64 s[8:9], s[8:9], s[10:11]
	s_cmpk_lg_u32 s101, 0x200
	s_cselect_b64 s[10:11], -1, 0
	s_and_b64 s[8:9], s[8:9], s[10:11]
	s_andn2_b64 vcc, exec, s[8:9]
	s_cbranch_vccnz .LBB0_13
	v_readlane_b32 s1, v254, 0
	s_cmp_lg_u32 s72, s1
	s_mov_b64 s[8:9], -1
	s_cbranch_scc0 .LBB0_411
	s_getreg_b32 s1, hwreg(HW_REG_XCC_ID, 0, 4)
	s_waitcnt vmcnt(0)
	s_waitcnt vmcnt(0) lgkmcnt(0)
	s_barrier
	s_mov_b64 s[8:9], exec
	v_readlane_b32 s10, v254, 24
	v_readlane_b32 s11, v254, 25
	s_and_b64 s[10:11], s[8:9], s[10:11]
	s_mov_b64 exec, s[10:11]
	s_cbranch_execz .LBB0_410
	s_add_i32 s4, 0, 0x21000
	v_mov_b32_e32 v0, s4
	s_waitcnt vmcnt(0) expcnt(0) lgkmcnt(0)
	ds_read_b32 v2, v0
	v_readlane_b32 s10, v254, 23
	s_and_b32 s1, s1, 15
	s_waitcnt lgkmcnt(0)
	v_cmp_ne_u32_e32 vcc, 0, v2
	v_mov_b32_e32 v0, s10
	ds_read_b32 v0, v0
	s_cbranch_vccnz .LBB0_374
	s_load_dwordx2 s[14:15], s[76:77], 0x4
	s_add_u32 s10, s78, 0x200200
	s_addc_u32 s11, s79, 0
	s_add_u32 s12, s78, 0x200400
	s_addc_u32 s13, s79, 0
	s_waitcnt lgkmcnt(0)
	s_mul_i32 s3, s14, s3
	s_add_u32 s14, s78, 0x200500
	s_mul_i32 s3, s3, s15
	s_addc_u32 s15, s79, 0
	s_add_u32 s16, s78, 0x200600
	s_addc_u32 s17, s79, 0
	s_add_u32 s18, s78, 0x200700
	s_addc_u32 s19, s79, 0
	s_add_u32 s20, s78, 0x200800
	s_addc_u32 s21, s79, 0
	s_add_u32 s22, s78, 0x200900
	s_addc_u32 s23, s79, 0
	s_add_u32 s24, s78, 0x200a00
	s_addc_u32 s25, s79, 0
	s_add_u32 s26, s78, 0x200b00
	s_addc_u32 s27, s79, 0
	s_add_u32 s28, s78, 0x200c00
	s_addc_u32 s29, s79, 0
	s_add_u32 s30, s78, 0x200d00
	s_addc_u32 s31, s79, 0
	s_add_u32 s34, s78, 0x200e00
	s_addc_u32 s35, s79, 0
	s_add_u32 s36, s78, 0x200f00
	s_addc_u32 s37, s79, 0
	s_add_u32 s38, s78, 0x201000
	s_addc_u32 s39, s79, 0
	s_add_u32 s40, s78, 0x201100
	s_addc_u32 s41, s79, 0
	s_add_u32 s52, s78, 0x201200
	s_addc_u32 s53, s79, 0
	s_add_u32 s80, s78, 0x201300
	s_addc_u32 s81, s79, 0
	s_mov_b32 s33, 1
	s_branch .LBB0_362
